# XCD-local seams keep the L1 invalidate only at S4 and S7 (where overlaid or in-place buffers are re-read); dropped in local paths of S1 S2 S3 S5 S8 and, in local mode, in the two row exchanges
# speedup vs baseline: 1.0255x; 1.0093x over previous
.Llb_spin_s1:
	global_load_dword v4, v3, s[4:5] sc1
	s_waitcnt vmcnt(0)
	v_cmp_ge_u32_e32 vcc, v4, v2
	s_cbranch_vccnz .Llb_acq_s1
	s_sleep 1
	s_add_i32 s99, s99, 1
	s_cmp_lt_u32 s99, 0x40000
	s_cbranch_scc1 .Llb_spin_s1
.Llb_acq_s1:
	s_waitcnt vmcnt(0)
.Llb_done_s1:
	s_or_b64 exec, exec, s[2:3]
	s_barrier

.Llb_spin_s2:
	global_load_dword v4, v3, s[4:5] sc1
	s_waitcnt vmcnt(0)
	v_cmp_ge_u32_e32 vcc, v4, v2
	s_cbranch_vccnz .Llb_acq_s2
	s_sleep 1
	s_add_i32 s99, s99, 1
	s_cmp_lt_u32 s99, 0x40000
	s_cbranch_scc1 .Llb_spin_s2
.Llb_acq_s2:
	s_waitcnt vmcnt(0)
.Llb_done_s2:
	s_or_b64 exec, exec, s[0:1]
	s_barrier

.Llb_g3_s3:
	global_load_dword v4, v5, s[10:11] sc1
	s_waitcnt vmcnt(0)
	v_cmp_le_u32_e32 vcc, s25, v4
	s_cbranch_vccnz .Llb_g3d_s3
	s_sleep 1
	s_add_i32 s99, s99, 1
	s_cmp_lt_u32 s99, 0x40000
	s_cbranch_scc1 .Llb_g3_s3
.Llb_g3d_s3:
	s_waitcnt vmcnt(0)
.Llb_done_s3:
	s_or_b64 exec, exec, s[2:3]
	s_barrier

.Llb_spin_s5:
	global_load_dword v4, v3, s[4:5] sc1
	s_waitcnt vmcnt(0)
	v_cmp_ge_u32_e32 vcc, v4, v2
	s_cbranch_vccnz .Llb_acq_s5
	s_sleep 1
	s_add_i32 s99, s99, 1
	s_cmp_lt_u32 s99, 0x40000
	s_cbranch_scc1 .Llb_spin_s5
.Llb_acq_s5:
	s_waitcnt vmcnt(0)
.Llb_done_s5:
	s_or_b64 exec, exec, s[0:1]
	s_barrier

.LBB0_595:
	s_waitcnt lgkmcnt(0)
	v_mov_b32_e32 v8, s88
	ds_read_b32 v8, v8 offset:8
	s_waitcnt lgkmcnt(0)
	v_readfirstlane_b32 s98, v8
	s_cmp_eq_u32 s98, 1
	s_cbranch_scc1 .Lxinv_skip_595
	buffer_inv sc1
.Lxinv_skip_595:
	s_waitcnt vmcnt(0)
.LBB0_596:
	s_or_b64 exec, exec, s[34:35]
	v_lshlrev_b32_e32 v8, 2, v244
	s_waitcnt lgkmcnt(1)
	v_ashrrev_i32_e32 v9, 31, v8
	v_lshl_add_u64 v[116:117], v[8:9], 3, s[42:43]
	s_barrier
	v_lshl_add_u64 v[8:9], v[116:117], 0, v[18:19]
	global_load_dwordx4 v[134:137], v[8:9], off
	global_load_dwordx4 v[138:141], v[8:9], off offset:16
	s_ashr_i32 s83, s82, 31
	s_or_b32 s34, s26, s91
	s_lshl_b64 s[0:1], s[82:83], 2
	v_readlane_b32 s35, v254, 59
	s_add_u32 s0, s35, s0
	v_readlane_b32 s35, v254, 60
	s_addc_u32 s1, s35, s1
	v_lshl_add_u64 v[2:3], v[116:117], 0, v[2:3]
	v_lshl_add_u64 v[4:5], v[116:117], 0, v[4:5]
	global_load_dword v133, v169, s[0:1]
	v_lshl_add_u64 v[124:125], v[116:117], 0, v[6:7]
	global_load_dwordx4 v[22:25], v[2:3], off offset:16
	global_load_dwordx4 v[18:21], v[2:3], off
	global_load_dwordx4 v[14:17], v[4:5], off offset:16
	s_waitcnt lgkmcnt(0)
	global_load_dwordx4 v[10:13], v[4:5], off
	global_load_dwordx4 v[6:9], v[124:125], off offset:16
	s_nop 0
	global_load_dwordx4 v[2:5], v[124:125], off
	s_waitcnt vmcnt(8)
	v_mov_b32_e32 v124, v134
	s_waitcnt vmcnt(7)
	v_mov_b32_e32 v125, v138
	v_mov_b32_e32 v130, v136
	v_mov_b32_e32 v131, v140
	v_pk_add_f32 v[124:125], v[124:125], v[130:131]
	v_max_f32_e32 v132, v141, v141
	v_add_f32_e32 v124, v124, v125
	ds_bpermute_b32 v125, v122, v124
	v_max_f32_e32 v134, v139, v139
	v_max_f32_e32 v130, v134, v132
	v_max3_f32 v130, v135, v137, v130
	ds_bpermute_b32 v131, v122, v130
	s_waitcnt lgkmcnt(1)
	v_add_f32_e32 v124, v124, v125
	ds_bpermute_b32 v125, v123, v124
	v_or_b32_e32 v132, s34, v244
	v_cmp_eq_u32_e32 vcc, 0, v132
	s_waitcnt lgkmcnt(1)
	v_max_f32_e32 v131, v131, v131
	v_max_f32_e32 v130, v130, v131
	s_waitcnt lgkmcnt(0)
	v_add_f32_e32 v124, v124, v125
	v_fmamk_f32 v124, v124, 0x3a800000, v240
	ds_bpermute_b32 v131, v123, v130
	v_mul_f32_e32 v125, 0x4b800000, v124
	v_cmp_gt_f32_e64 s[0:1], s96, v124
	s_nop 1
	v_cndmask_b32_e64 v124, v124, v125, s[0:1]
	v_rsq_f32_e32 v124, v124
	s_waitcnt lgkmcnt(0)
	v_max_f32_e32 v125, v131, v131
	v_max_f32_e32 v125, v130, v125
	v_mul_f32_e32 v130, 0x45800000, v124
	v_cndmask_b32_e64 v124, v124, v130, s[0:1]
	s_waitcnt vmcnt(6)
	v_fma_f32 v125, v125, v124, v133
	s_and_saveexec_b64 s[0:1], vcc
	s_cbranch_execz .LBB0_598
	v_mul_f32_e32 v132, 0x3c010204, v125
	v_lshl_add_u64 v[130:131], v[176:177], 2, s[6:7]
	global_store_dword v[130:131], v132, off

.Llb_spin_s8:
	global_load_dword v4, v3, s[4:5] sc1
	s_waitcnt vmcnt(0)
	v_cmp_ge_u32_e32 vcc, v4, v2
	s_cbranch_vccnz .Llb_acq_s8
	s_sleep 1
	s_add_i32 s99, s99, 1
	s_cmp_lt_u32 s99, 0x40000
	s_cbranch_scc1 .Llb_spin_s8
.Llb_acq_s8:
	s_waitcnt vmcnt(0)
.Llb_done_s8:
	s_or_b64 exec, exec, s[0:1]
	s_barrier

.LBB0_748:
	s_waitcnt lgkmcnt(0)
	v_mov_b32_e32 v2, s88
	ds_read_b32 v2, v2 offset:8
	s_waitcnt lgkmcnt(0)
	v_readfirstlane_b32 s98, v2
	s_cmp_eq_u32 s98, 1
	s_cbranch_scc1 .Lxinv_skip_748
	buffer_inv sc1
.Lxinv_skip_748:
	s_waitcnt vmcnt(0)
.LBB0_749:
	s_or_b64 exec, exec, s[6:7]
	v_lshlrev_b32_e32 v2, 2, v225
	s_waitcnt lgkmcnt(0)
	v_ashrrev_i32_e32 v3, 31, v2
	v_lshl_add_u64 v[2:3], v[2:3], 2, s[30:31]
	s_barrier
	v_lshl_add_u64 v[4:5], v[2:3], 0, v[196:197]
	global_load_dwordx4 v[8:11], v[4:5], off
	v_lshl_add_u64 v[4:5], v[2:3], 0, v[176:177]
	global_load_dwordx4 v[12:15], v[4:5], off
	v_lshl_add_u64 v[4:5], v[2:3], 0, v[168:169]
	global_load_dwordx4 v[154:157], v[4:5], off
	v_lshl_add_u64 v[4:5], v[2:3], 0, v[160:161]
	global_load_dwordx4 v[158:161], v[4:5], off
	v_lshl_add_u64 v[4:5], v[2:3], 0, v[152:153]
	global_load_dwordx4 v[162:165], v[4:5], off
	v_lshl_add_u64 v[4:5], v[2:3], 0, v[148:149]
	global_load_dwordx4 v[166:169], v[4:5], off
	v_lshl_add_u64 v[6:7], v[2:3], 0, v[150:151]
	v_lshl_add_u64 v[0:1], v[2:3], 0, v[0:1]
	global_load_dwordx4 v[170:173], v[6:7], off
	global_load_dwordx4 v[174:177], v[0:1], off
	s_add_i32 s64, s64, s83
	v_add_u32_e32 v4, s64, v223
	s_add_u32 s64, s71, s66
	v_ashrrev_i32_e32 v5, 31, v4
	v_readlane_b32 s48, v254, 0
	s_addc_u32 s65, s72, s67
	v_lshlrev_b64 v[2:3], 2, v[4:5]
	v_readlane_b32 s52, v254, 4
	v_readlane_b32 s53, v254, 5
	s_add_u32 s66, s73, s66
	v_add_u32_e32 v132, 0x80, v4
	v_lshl_add_u64 v[0:1], s[52:53], 0, v[2:3]
	v_lshl_add_u64 v[4:5], s[64:65], 0, v[2:3]
	s_addc_u32 s67, s74, s67
	global_load_dwordx4 v[178:181], v[0:1], off offset:16
	global_load_dwordx4 v[192:195], v[0:1], off
	global_load_dwordx4 v[196:199], v[4:5], off offset:16
	global_load_dwordx4 v[200:203], v[4:5], off
	v_lshl_add_u64 v[4:5], s[66:67], 0, v[2:3]
	global_load_dwordx4 v[0:3], v[4:5], off offset:16
	s_nop 0
	global_load_dwordx4 v[4:7], v[4:5], off
	v_mov_b64_e32 v[182:183], s[58:59]
	v_readlane_b32 s54, v254, 6
	v_readlane_b32 s55, v254, 7
	v_ashrrev_i32_e32 v133, 31, v132
	v_readlane_b32 s49, v254, 1
	v_readlane_b32 s50, v254, 2
	v_readlane_b32 s51, v254, 3
	s_waitcnt vmcnt(13)
	v_mov_b32_e32 v134, v9
	v_mov_b32_e32 v135, v10
	v_mov_b32_e32 v9, v11
	s_waitcnt vmcnt(12)
	v_mov_b32_e32 v10, v13
	v_mov_b32_e32 v11, v14
	v_mov_b32_e32 v13, v15
	s_waitcnt vmcnt(11)
	v_mov_b32_e32 v14, v155
	v_mov_b32_e32 v15, v156
	v_mov_b32_e32 v155, v157
	s_waitcnt vmcnt(10)
	v_mov_b32_e32 v148, v159
	v_mov_b32_e32 v149, v160
	v_mov_b32_e32 v159, v161
	s_waitcnt vmcnt(9)
	v_mov_b32_e32 v150, v163
	v_mov_b32_e32 v151, v164
	v_mov_b32_e32 v163, v165
	v_pk_add_f32 v[8:9], v[134:135], v[8:9]
	v_pk_add_f32 v[10:11], v[10:11], v[12:13]
	v_pk_add_f32 v[12:13], v[14:15], v[154:155]
	v_pk_add_f32 v[14:15], v[148:149], v[158:159]
	v_pk_add_f32 v[134:135], v[150:151], v[162:163]
	v_mov_b32_e32 v150, v10
	v_mov_b32_e32 v151, v8
	v_mov_b32_e32 v8, v11
	v_mov_b32_e32 v10, v14
	v_mov_b32_e32 v11, v12
	v_mov_b32_e32 v12, v15
	v_pk_add_f32 v[8:9], v[150:151], v[8:9]
	v_pk_add_f32 v[10:11], v[10:11], v[12:13]
	ds_bpermute_b32 v13, v222, v9
	ds_bpermute_b32 v12, v222, v8
	ds_bpermute_b32 v15, v222, v11
	ds_bpermute_b32 v14, v222, v10
	s_waitcnt vmcnt(8)
	v_mov_b32_e32 v152, v167
	v_mov_b32_e32 v153, v168
	s_waitcnt lgkmcnt(2)
	v_pk_add_f32 v[8:9], v[8:9], v[12:13]
	ds_bpermute_b32 v13, v224, v9
	ds_bpermute_b32 v12, v224, v8
	s_waitcnt lgkmcnt(2)
	v_pk_add_f32 v[10:11], v[10:11], v[14:15]
	ds_bpermute_b32 v15, v224, v11
	ds_bpermute_b32 v14, v224, v10
	v_mov_b32_e32 v167, v169
	s_waitcnt lgkmcnt(2)
	v_pk_add_f32 v[8:9], v[8:9], v[12:13]
	v_pk_add_f32 v[148:149], v[152:153], v[166:167]
	v_pk_fma_f32 v[8:9], v[8:9], s[56:57], v[182:183] op_sel_hi:[1,0,0]
	v_mov_b32_e32 v150, v148
	v_mul_f32_e32 v12, 0x4b800000, v9
	v_cmp_gt_f32_e32 vcc, s91, v9
	v_mov_b32_e32 v151, v134
	v_mov_b32_e32 v134, v149
	v_cndmask_b32_e32 v9, v9, v12, vcc
	s_waitcnt lgkmcnt(0)
	v_pk_add_f32 v[10:11], v[10:11], v[14:15]
	v_rsq_f32_e32 v9, v9
	v_pk_add_f32 v[134:135], v[150:151], v[134:135]
	v_pk_fma_f32 v[10:11], v[10:11], s[56:57], v[182:183] op_sel_hi:[1,0,0]
	v_mul_f32_e32 v13, 0x4b800000, v8
	v_cmp_gt_f32_e64 s[0:1], s91, v8
	ds_bpermute_b32 v149, v222, v135
	ds_bpermute_b32 v148, v222, v134
	v_mul_f32_e32 v14, 0x4b800000, v11
	v_cndmask_b32_e64 v8, v8, v13, s[0:1]
	v_cmp_gt_f32_e64 s[6:7], s91, v11
	v_rsq_f32_e32 v12, v8
	s_waitcnt vmcnt(3)
	v_pk_add_f32 v[158:159], v[198:199], 1.0 op_sel_hi:[1,0]
	v_cndmask_b32_e64 v8, v11, v14, s[6:7]
	v_rsq_f32_e32 v13, v8
	v_mul_f32_e32 v8, 0x45800000, v9
	v_cndmask_b32_e32 v152, v9, v8, vcc
	v_mul_f32_e32 v8, 0x4b800000, v10
	v_cmp_gt_f32_e32 vcc, s91, v10
	v_mul_f32_e32 v14, 0x45800000, v12
	v_cndmask_b32_e64 v150, v12, v14, s[0:1]
	v_cndmask_b32_e32 v8, v10, v8, vcc
	v_rsq_f32_e32 v151, v8
	s_waitcnt lgkmcnt(0)
	v_pk_add_f32 v[8:9], v[134:135], v[148:149]
	ds_bpermute_b32 v11, v224, v9
	ds_bpermute_b32 v10, v224, v8
	v_mul_f32_e32 v12, 0x45800000, v13
	v_cndmask_b32_e64 v134, v13, v12, s[6:7]
	v_mov_b32_e32 v12, v175
	v_mov_b32_e32 v13, v176
	s_waitcnt lgkmcnt(0)
	v_pk_add_f32 v[8:9], v[8:9], v[10:11]
	v_mov_b32_e32 v11, v172
	v_pk_fma_f32 v[8:9], v[8:9], s[56:57], v[182:183] op_sel_hi:[1,0,0]
	v_mov_b32_e32 v175, v177
	v_mul_f32_e32 v10, 0x4b800000, v9
	v_cmp_gt_f32_e64 s[0:1], s91, v9
	v_pk_add_f32 v[12:13], v[12:13], v[174:175]
	v_cmp_gt_f32_e64 s[6:7], s91, v8
	v_cndmask_b32_e64 v9, v9, v10, s[0:1]
	v_mov_b32_e32 v10, v171
	v_mov_b32_e32 v171, v173
	v_pk_add_f32 v[10:11], v[10:11], v[170:171]
	v_mov_b32_e32 v14, v12
	v_mov_b32_e32 v15, v10
	v_mov_b32_e32 v10, v13
	v_pk_add_f32 v[10:11], v[14:15], v[10:11]
	ds_bpermute_b32 v13, v222, v11
	ds_bpermute_b32 v12, v222, v10
	v_rsq_f32_e32 v149, v9
	v_mul_f32_e32 v9, 0x4b800000, v8
	v_cndmask_b32_e64 v8, v8, v9, s[6:7]
	v_rsq_f32_e32 v15, v8
	s_waitcnt lgkmcnt(0)
	v_pk_add_f32 v[8:9], v[10:11], v[12:13]
	ds_bpermute_b32 v11, v224, v9
	ds_bpermute_b32 v10, v224, v8
	v_mul_f32_e32 v135, 0x45800000, v151
	v_cndmask_b32_e32 v148, v151, v135, vcc
	v_mul_f32_e32 v12, 0x45800000, v149
	v_pk_add_f32 v[160:161], v[196:197], 1.0 op_sel_hi:[1,0]
	s_waitcnt lgkmcnt(0)
	v_pk_add_f32 v[8:9], v[8:9], v[10:11]
	v_cndmask_b32_e64 v14, v149, v12, s[0:1]
	v_pk_fma_f32 v[8:9], v[8:9], s[56:57], v[182:183] op_sel_hi:[1,0,0]
	s_waitcnt vmcnt(2)
	v_pk_add_f32 v[156:157], v[200:201], 1.0 op_sel_hi:[1,0]
	v_mul_f32_e32 v10, 0x4b800000, v9
	v_cmp_gt_f32_e32 vcc, s91, v9
	v_cmp_gt_f32_e64 s[0:1], s91, v8
	v_pk_mul_f32 v[158:159], v[180:181], v[158:159]
	v_cndmask_b32_e32 v9, v9, v10, vcc
	v_rsq_f32_e32 v9, v9
	v_mul_f32_e32 v10, 0x4b800000, v8
	v_pk_mul_f32 v[160:161], v[178:179], v[160:161]
	v_pk_mul_f32 v[120:121], v[120:121], v[152:153] op_sel_hi:[1,0]
	v_pk_mul_f32 v[122:123], v[122:123], v[152:153] op_sel_hi:[1,0]
	v_cndmask_b32_e64 v8, v8, v10, s[0:1]
	v_mul_f32_e32 v10, 0x45800000, v9
	v_pk_mul_f32 v[156:157], v[192:193], v[156:157]
	v_lshl_add_u64 v[162:163], s[54:55], 0, v[240:241]
	s_waitcnt vmcnt(1)
	v_pk_fma_f32 v[122:123], v[122:123], v[158:159], v[2:3]
	v_pk_fma_f32 v[120:121], v[120:121], v[160:161], v[0:1]
	v_pk_mul_f32 v[108:109], v[108:109], v[150:151] op_sel_hi:[1,0]
	v_cndmask_b32_e32 v10, v9, v10, vcc
	global_store_dwordx4 v240, v[120:123], s[54:55] offset:16
	v_pk_mul_f32 v[104:105], v[104:105], v[150:151] op_sel_hi:[1,0]
	v_pk_mul_f32 v[106:107], v[106:107], v[150:151] op_sel_hi:[1,0]
	s_waitcnt vmcnt(1)
	v_pk_fma_f32 v[120:121], v[108:109], v[156:157], v[4:5]
	v_add_co_u32_e32 v108, vcc, s68, v162
	v_pk_fma_f32 v[106:107], v[106:107], v[158:159], v[2:3]
	s_nop 0
	v_addc_co_u32_e32 v109, vcc, 0, v163, vcc
	v_pk_fma_f32 v[104:105], v[104:105], v[160:161], v[0:1]
	v_pk_mul_f32 v[92:93], v[92:93], v[134:135] op_sel_hi:[1,0]
	global_store_dwordx4 v[108:109], v[104:107], off offset:16
	v_pk_mul_f32 v[88:89], v[88:89], v[134:135] op_sel_hi:[1,0]
	v_pk_mul_f32 v[90:91], v[90:91], v[134:135] op_sel_hi:[1,0]
	v_pk_fma_f32 v[104:105], v[92:93], v[156:157], v[4:5]
	v_add_co_u32_e32 v92, vcc, s95, v162
	v_pk_fma_f32 v[90:91], v[90:91], v[158:159], v[2:3]
	s_nop 0
	v_addc_co_u32_e32 v93, vcc, 0, v163, vcc
	v_pk_fma_f32 v[88:89], v[88:89], v[160:161], v[0:1]
	v_pk_mul_f32 v[76:77], v[76:77], v[148:149] op_sel_hi:[1,0]
	global_store_dwordx4 v[92:93], v[88:91], off offset:16
	v_pk_mul_f32 v[72:73], v[72:73], v[148:149] op_sel_hi:[1,0]
	v_pk_mul_f32 v[74:75], v[74:75], v[148:149] op_sel_hi:[1,0]
	v_pk_fma_f32 v[88:89], v[76:77], v[156:157], v[4:5]
	v_add_co_u32_e32 v76, vcc, s59, v162
	v_pk_fma_f32 v[74:75], v[74:75], v[158:159], v[2:3]
	s_nop 0
	v_addc_co_u32_e32 v77, vcc, 0, v163, vcc
	v_pk_fma_f32 v[72:73], v[72:73], v[160:161], v[0:1]
	v_mul_f32_e32 v12, 0x45800000, v15
	global_store_dwordx4 v[76:77], v[72:75], off offset:16
	v_cndmask_b32_e64 v12, v15, v12, s[6:7]
	v_rsq_f32_e32 v8, v8
	v_add_co_u32_e32 v72, vcc, s88, v162
	v_pk_add_f32 v[154:155], v[202:203], 1.0 op_sel_hi:[1,0]
	s_nop 0
	v_addc_co_u32_e32 v73, vcc, 0, v163, vcc
	v_add_co_u32_e32 v74, vcc, s89, v162
	v_pk_mul_f32 v[40:41], v[40:41], v[12:13] op_sel_hi:[1,0]
	v_pk_mul_f32 v[42:43], v[42:43], v[12:13] op_sel_hi:[1,0]
	v_pk_mul_f32 v[154:155], v[194:195], v[154:155]
	v_pk_mul_f32 v[78:79], v[78:79], v[148:149] op_sel_hi:[1,0]
	v_addc_co_u32_e32 v75, vcc, 0, v163, vcc
	v_pk_fma_f32 v[42:43], v[158:159], v[42:43], v[2:3]
	v_pk_fma_f32 v[40:41], v[160:161], v[40:41], v[0:1]
	v_pk_fma_f32 v[90:91], v[78:79], v[154:155], v[6:7]
	global_store_dwordx4 v[74:75], v[40:43], off offset:16
	v_add_co_u32_e32 v78, vcc, s90, v162
	s_nop 0
	v_pk_mul_f32 v[40:41], v[146:147], v[10:11] op_sel_hi:[1,0]
	v_pk_mul_f32 v[42:43], v[144:145], v[10:11] op_sel_hi:[1,0]
	v_pk_fma_f32 v[40:41], v[156:157], v[40:41], v[4:5]
	v_pk_fma_f32 v[42:43], v[154:155], v[42:43], v[6:7]
	v_addc_co_u32_e32 v79, vcc, 0, v163, vcc
	v_mul_f32_e32 v9, 0x45800000, v8
	global_store_dwordx4 v[78:79], v[40:43], off
	v_cndmask_b32_e64 v8, v8, v9, s[0:1]
	s_mov_b32 s0, 0xb0000
	v_pk_mul_f32 v[40:41], v[138:139], v[10:11] op_sel_hi:[1,0]
	v_pk_mul_f32 v[42:43], v[136:137], v[10:11] op_sel_hi:[1,0]
	v_pk_fma_f32 v[40:41], v[160:161], v[40:41], v[0:1]
	v_pk_fma_f32 v[42:43], v[158:159], v[42:43], v[2:3]
	v_pk_mul_f32 v[124:125], v[124:125], v[152:153] op_sel_hi:[1,0]
	v_pk_mul_f32 v[126:127], v[126:127], v[152:153] op_sel_hi:[1,0]
	v_pk_mul_f32 v[110:111], v[110:111], v[150:151] op_sel_hi:[1,0]
	v_pk_mul_f32 v[94:95], v[94:95], v[134:135] op_sel_hi:[1,0]
	global_store_dwordx4 v[76:77], v[88:91], off
	v_pk_mul_f32 v[60:61], v[60:61], v[14:15] op_sel_hi:[1,0]
	v_pk_mul_f32 v[62:63], v[62:63], v[14:15] op_sel_hi:[1,0]
	v_pk_mul_f32 v[44:45], v[44:45], v[12:13] op_sel_hi:[1,0]
	v_pk_mul_f32 v[46:47], v[46:47], v[12:13] op_sel_hi:[1,0]
	global_store_dwordx4 v[78:79], v[40:43], off offset:16
	v_add_co_u32_e32 v88, vcc, s0, v162
	s_nop 0
	v_pk_mul_f32 v[40:41], v[142:143], v[8:9] op_sel_hi:[1,0]
	v_pk_mul_f32 v[42:43], v[130:131], v[8:9] op_sel_hi:[1,0]
	v_pk_fma_f32 v[126:127], v[126:127], v[154:155], v[6:7]
	v_pk_fma_f32 v[124:125], v[124:125], v[156:157], v[4:5]
	v_pk_fma_f32 v[122:123], v[110:111], v[154:155], v[6:7]
	v_pk_fma_f32 v[106:107], v[94:95], v[154:155], v[6:7]
	v_pk_fma_f32 v[62:63], v[154:155], v[62:63], v[6:7]
	v_pk_fma_f32 v[60:61], v[156:157], v[60:61], v[4:5]
	v_pk_mul_f32 v[56:57], v[56:57], v[14:15] op_sel_hi:[1,0]
	v_pk_mul_f32 v[58:59], v[58:59], v[14:15] op_sel_hi:[1,0]
	v_pk_fma_f32 v[46:47], v[154:155], v[46:47], v[6:7]
	v_pk_fma_f32 v[44:45], v[156:157], v[44:45], v[4:5]
	v_pk_fma_f32 v[6:7], v[154:155], v[42:43], v[6:7]
	v_pk_fma_f32 v[4:5], v[156:157], v[40:41], v[4:5]
	v_addc_co_u32_e32 v89, vcc, 0, v163, vcc
	v_pk_fma_f32 v[58:59], v[58:59], v[158:159], v[2:3]
	v_pk_fma_f32 v[56:57], v[56:57], v[160:161], v[0:1]
	global_store_dwordx4 v[88:89], v[4:7], off
	global_store_dwordx4 v[72:73], v[56:59], off offset:16
	global_store_dwordx4 v240, v[124:127], s[54:55]
	v_pk_mul_f32 v[4:5], v[140:141], v[8:9] op_sel_hi:[1,0]
	v_pk_mul_f32 v[6:7], v[128:129], v[8:9] op_sel_hi:[1,0]
	v_pk_fma_f32 v[0:1], v[160:161], v[4:5], v[0:1]
	v_pk_fma_f32 v[2:3], v[158:159], v[6:7], v[2:3]
	v_lshlrev_b64 v[56:57], 2, v[132:133]
	global_store_dwordx4 v[108:109], v[120:123], off
	global_store_dwordx4 v[92:93], v[104:107], off
	global_store_dwordx4 v[72:73], v[60:63], off
	global_store_dwordx4 v[74:75], v[44:47], off
	global_store_dwordx4 v[88:89], v[0:3], off offset:16
	v_lshl_add_u64 v[40:41], s[64:65], 0, v[56:57]
	global_load_dwordx4 v[0:3], v[40:41], off
	v_lshl_add_u64 v[44:45], s[52:53], 0, v[56:57]
	global_load_dwordx4 v[4:7], v[44:45], off
	s_nop 0
	global_load_dwordx4 v[40:43], v[40:41], off offset:16
	s_nop 0
	global_load_dwordx4 v[44:47], v[44:45], off offset:16
	v_lshl_add_u64 v[60:61], s[66:67], 0, v[56:57]
	global_load_dwordx4 v[56:59], v[60:61], off
	s_nop 0
	global_load_dwordx4 v[60:63], v[60:61], off offset:16
	s_and_b64 vcc, exec, s[4:5]
	s_mov_b64 s[0:1], -1
	s_waitcnt vmcnt(5)
	v_pk_add_f32 v[2:3], v[2:3], 1.0 op_sel_hi:[1,0]
	v_pk_add_f32 v[0:1], v[0:1], 1.0 op_sel_hi:[1,0]
	s_waitcnt vmcnt(4)
	v_pk_mul_f32 v[6:7], v[6:7], v[2:3]
	v_pk_mul_f32 v[4:5], v[4:5], v[0:1]
	s_waitcnt vmcnt(3)
	v_pk_add_f32 v[0:1], v[42:43], 1.0 op_sel_hi:[1,0]
	v_pk_add_f32 v[2:3], v[40:41], 1.0 op_sel_hi:[1,0]
	s_waitcnt vmcnt(2)
	v_pk_mul_f32 v[40:41], v[46:47], v[0:1]
	v_pk_mul_f32 v[42:43], v[44:45], v[2:3]
	v_pk_mul_f32 v[2:3], v[118:119], v[152:153] op_sel_hi:[1,0]
	v_pk_mul_f32 v[0:1], v[116:117], v[152:153] op_sel_hi:[1,0]
	s_waitcnt vmcnt(1)
	v_pk_fma_f32 v[2:3], v[2:3], v[6:7], v[58:59]
	v_pk_fma_f32 v[0:1], v[0:1], v[4:5], v[56:57]
	global_store_dwordx4 v240, v[0:3], s[54:55] offset:512
	s_nop 1
	v_pk_mul_f32 v[2:3], v[114:115], v[152:153] op_sel_hi:[1,0]
	v_pk_mul_f32 v[0:1], v[112:113], v[152:153] op_sel_hi:[1,0]
	s_waitcnt vmcnt(1)
	v_pk_fma_f32 v[2:3], v[2:3], v[40:41], v[62:63]
	v_pk_fma_f32 v[0:1], v[0:1], v[42:43], v[60:61]
	global_store_dwordx4 v240, v[0:3], s[54:55] offset:528
	s_nop 1
	v_pk_mul_f32 v[2:3], v[102:103], v[150:151] op_sel_hi:[1,0]
	v_pk_mul_f32 v[0:1], v[100:101], v[150:151] op_sel_hi:[1,0]
	v_pk_fma_f32 v[2:3], v[2:3], v[6:7], v[58:59]
	v_pk_fma_f32 v[0:1], v[0:1], v[4:5], v[56:57]
	global_store_dwordx4 v[108:109], v[0:3], off offset:512
	s_nop 1
	v_pk_mul_f32 v[2:3], v[98:99], v[150:151] op_sel_hi:[1,0]
	v_pk_mul_f32 v[0:1], v[96:97], v[150:151] op_sel_hi:[1,0]
	v_pk_fma_f32 v[2:3], v[2:3], v[40:41], v[62:63]
	v_pk_fma_f32 v[0:1], v[0:1], v[42:43], v[60:61]
	global_store_dwordx4 v[108:109], v[0:3], off offset:528
	s_nop 1
	v_pk_mul_f32 v[2:3], v[86:87], v[134:135] op_sel_hi:[1,0]
	v_pk_mul_f32 v[0:1], v[84:85], v[134:135] op_sel_hi:[1,0]
	v_pk_fma_f32 v[2:3], v[2:3], v[6:7], v[58:59]
	v_pk_fma_f32 v[0:1], v[0:1], v[4:5], v[56:57]
	global_store_dwordx4 v[92:93], v[0:3], off offset:512
	s_nop 1
	v_pk_mul_f32 v[2:3], v[82:83], v[134:135] op_sel_hi:[1,0]
	v_pk_mul_f32 v[0:1], v[80:81], v[134:135] op_sel_hi:[1,0]
	v_pk_fma_f32 v[2:3], v[2:3], v[40:41], v[62:63]
	v_pk_fma_f32 v[0:1], v[0:1], v[42:43], v[60:61]
	global_store_dwordx4 v[92:93], v[0:3], off offset:528
	s_nop 1
	v_pk_mul_f32 v[2:3], v[70:71], v[148:149] op_sel_hi:[1,0]
	v_pk_mul_f32 v[0:1], v[68:69], v[148:149] op_sel_hi:[1,0]
	v_pk_fma_f32 v[2:3], v[2:3], v[6:7], v[58:59]
	v_pk_fma_f32 v[0:1], v[0:1], v[4:5], v[56:57]
	global_store_dwordx4 v[76:77], v[0:3], off offset:512
	s_nop 1
	v_pk_mul_f32 v[2:3], v[66:67], v[148:149] op_sel_hi:[1,0]
	v_pk_mul_f32 v[0:1], v[64:65], v[148:149] op_sel_hi:[1,0]
	v_pk_fma_f32 v[2:3], v[2:3], v[40:41], v[62:63]
	v_pk_fma_f32 v[0:1], v[0:1], v[42:43], v[60:61]
	global_store_dwordx4 v[76:77], v[0:3], off offset:528
	s_nop 1
	v_pk_mul_f32 v[2:3], v[54:55], v[14:15] op_sel_hi:[1,0]
	v_pk_mul_f32 v[0:1], v[52:53], v[14:15] op_sel_hi:[1,0]
	v_pk_fma_f32 v[2:3], v[2:3], v[6:7], v[58:59]
	v_pk_fma_f32 v[0:1], v[0:1], v[4:5], v[56:57]
	global_store_dwordx4 v[72:73], v[0:3], off offset:512
	s_nop 1
	v_pk_mul_f32 v[2:3], v[50:51], v[14:15] op_sel_hi:[1,0]
	v_pk_mul_f32 v[0:1], v[48:49], v[14:15] op_sel_hi:[1,0]
	v_pk_fma_f32 v[2:3], v[2:3], v[40:41], v[62:63]
	v_pk_fma_f32 v[0:1], v[0:1], v[42:43], v[60:61]
	global_store_dwordx4 v[72:73], v[0:3], off offset:528
	s_nop 1
	v_pk_mul_f32 v[2:3], v[38:39], v[12:13] op_sel_hi:[1,0]
	v_pk_mul_f32 v[0:1], v[36:37], v[12:13] op_sel_hi:[1,0]
	v_pk_fma_f32 v[2:3], v[2:3], v[6:7], v[58:59]
	v_pk_fma_f32 v[0:1], v[0:1], v[4:5], v[56:57]
	global_store_dwordx4 v[74:75], v[0:3], off offset:512
	s_nop 1
	v_pk_mul_f32 v[2:3], v[34:35], v[12:13] op_sel_hi:[1,0]
	v_pk_mul_f32 v[0:1], v[32:33], v[12:13] op_sel_hi:[1,0]
	v_pk_fma_f32 v[2:3], v[2:3], v[40:41], v[62:63]
	v_pk_fma_f32 v[0:1], v[0:1], v[42:43], v[60:61]
	global_store_dwordx4 v[74:75], v[0:3], off offset:528
	s_nop 1
	v_pk_mul_f32 v[2:3], v[22:23], v[10:11] op_sel_hi:[1,0]
	v_pk_mul_f32 v[0:1], v[20:21], v[10:11] op_sel_hi:[1,0]
	v_pk_fma_f32 v[2:3], v[2:3], v[6:7], v[58:59]
	v_pk_fma_f32 v[0:1], v[0:1], v[4:5], v[56:57]
	global_store_dwordx4 v[78:79], v[0:3], off offset:512
	s_nop 1
	v_pk_mul_f32 v[2:3], v[18:19], v[10:11] op_sel_hi:[1,0]
	v_pk_mul_f32 v[0:1], v[16:17], v[10:11] op_sel_hi:[1,0]
	v_pk_fma_f32 v[2:3], v[2:3], v[40:41], v[62:63]
	v_pk_fma_f32 v[0:1], v[0:1], v[42:43], v[60:61]
	global_store_dwordx4 v[78:79], v[0:3], off offset:528
	s_nop 1
	v_pk_mul_f32 v[2:3], v[26:27], v[8:9] op_sel_hi:[1,0]
	v_pk_mul_f32 v[0:1], v[30:31], v[8:9] op_sel_hi:[1,0]
	v_pk_fma_f32 v[2:3], v[2:3], v[6:7], v[58:59]
	v_pk_fma_f32 v[0:1], v[0:1], v[4:5], v[56:57]
	global_store_dwordx4 v[88:89], v[0:3], off offset:512
	s_nop 1
	v_pk_mul_f32 v[2:3], v[24:25], v[8:9] op_sel_hi:[1,0]
	v_pk_mul_f32 v[0:1], v[28:29], v[8:9] op_sel_hi:[1,0]
	v_pk_fma_f32 v[2:3], v[2:3], v[40:41], v[62:63]
	v_pk_fma_f32 v[0:1], v[0:1], v[42:43], v[60:61]
	global_store_dwordx4 v[88:89], v[0:3], off offset:528
	s_cbranch_vccnz .LBB0_709
	v_readlane_b32 s0, v254, 41
	v_readlane_b32 s1, v254, 42
	s_andn2_b64 vcc, exec, s[0:1]
	s_cbranch_vccnz .LBB0_708
	s_barrier
	s_branch .LBB0_708
